# attention unit prologues: mem cross-attention K/V tile-0 loads issued with the Q loads; MLA key tile 1 loaded with the unit prologue loads
# baseline (speedup 1.0000x reference)
; #define LAS __attribute__((address_space(3)))
; #define ATT_LSTORE(buf) do { LAS unsigned char* b_ = lds + (buf) * BUF; \
;         _Pragma("unroll") for (int i = 0; i < KPT; ++i) { if (KCH % NTHREADS == 0 || tid + i * NTHREADS < KCH) *(LAS u32x4*)(b_ + klo[i]) = kreg[i]; } \
;         _Pragma("unroll") for (int i = 0; i < VPT; ++i) *(LAS u32x4*)(b_ + vlo[i]) = vreg[i]; } while (0)
; template <int DQK, int DV, int FLAGS, int qp, int kp, int vts, int op> ...
;     ...
;     f32x16 o[NDB];
; #pragma unroll
;     for (int d = 0; d < NDB; ++d)
; #pragma unroll
;         for (int r = 0; r < 16; ++r) o[d][r] = 0.f;
;     float m = (FLAGS & AF_ROBUST) ? -1e30f : 0.f, l = 0.f;
;     f32x16 negm;
; #pragma unroll
;     for (int r = 0; r < 16; ++r) negm[r] = 0.f;
;     u32x4 kreg[KPT], vreg[VPT];
;     unsigned kgo[KPT], vgo[VPT], klo[KPT], vlo[VPT];
; #pragma unroll
;     for (int i = 0; i < KPT; ++i) { const int c = tid + i * NTHREADS; const int row = c / KC, cc = c % KC; kgo[i] = (unsigned)(row * kp + cc * 8) * 2u; klo[i] = (unsigned)(row * KROW + cc * 16); }
; #pragma unroll
;     for (int i = 0; i < VPT; ++i) { const int c = tid + i * NTHREADS; const int d = c >> 3, cc = c & 7; vgo[i] = (unsigned)(d * vts + cc * 8) * 2u; vlo[i] = (unsigned)(KT_BYTES + d * VROW + cc * 16); }
;     ...
;     ATT_GLOAD((FLAGS & AF_REV) ? kt_hi - 1 : kt_lo); ATT_LSTORE(0);
;     __syncthreads();
;     ...
;             for (int c = 0; c < ND0 / 2; ++c) {
;                 if (c + 1 < ND0 / 2) {
; #pragma unroll
;                     for (int i = 0; i < 2; ++i) { kf[(c + 1) & 1][2 * i] = *(const LAS bf16x8*)(kb + (2 * c + 2 + i) * 32); kf[(c + 1) & 1][2 * i + 1] = *(const LAS bf16x8*)(kb + 32 * KROW + (2 * c + 2 + i) * 32); }
;                 }
; #pragma unroll
;                 for (int i = 0; i < 2; ++i) {
;                     p0 = __builtin_amdgcn_mfma_f32_32x32x16_bf16(kf[c & 1][2 * i], qr[2 * c + i], p0, 0, 0, 0);
;                     p1 = __builtin_amdgcn_mfma_f32_32x32x16_bf16(kf[c & 1][2 * i + 1], qr[2 * c + i], p1, 0, 0, 0);
;                 }
;                 __builtin_amdgcn_sched_barrier(0);
;             }
;             if (more) ATT_GLOAD((FLAGS & AF_REV) ? t - 1 : t + 1);
.LBB0_530:
	s_or_b64 exec, exec, s[14:15]
	s_add_u32 s98, s12, 0x18000
	s_addc_u32 s99, s13, 0
	global_load_dwordx4 v[214:217], v16, s[98:99]
	s_and_saveexec_b64 s[14:15], s[10:11]
	global_load_dwordx4 v[218:221], v18, s[98:99]
	s_or_b64 exec, exec, s[14:15]
	s_lshl_b32 s14, s20, 24
	v_readlane_b32 s0, v252, 39
	v_readlane_b32 s1, v252, 40
	s_add_u32 s12, s0, s14
	s_addc_u32 s13, s1, 0
	s_lshl_b32 s15, s86, 21
	v_lshlrev_b32_e32 v15, 4, v17
	s_add_u32 s12, s12, s15
	v_ashrrev_i32_e32 v23, 3, v17
	v_and_b32_e32 v22, 0x70, v15
	s_addc_u32 s13, s13, 0
	v_lshl_or_b32 v20, v23, 15, v22
	global_load_dwordx4 v[148:151], v20, s[12:13]
	global_load_dwordx4 v[222:225], v20, s[12:13] offset:128
	v_mad_u64_u32 v[14:15], s[12:13], v14, s25, v[16:17]
	s_and_saveexec_b64 s[12:13], s[8:9]
	s_cbranch_execz .LBB0_532
	v_add_u32_e32 v15, 0, v14
	s_waitcnt vmcnt(3)
	ds_write_b128 v15, v[140:143]
.LBB0_532:
	s_or_b64 exec, exec, s[12:13]
	v_mad_u64_u32 v[172:173], s[12:13], v21, s25, v[18:19]
	s_and_saveexec_b64 s[12:13], s[10:11]
	s_cbranch_execz .LBB0_534
	v_add_u32_e32 v15, 0, v172
	s_waitcnt vmcnt(4)
	ds_write_b128 v15, v[144:147]
.LBB0_534:
	s_or_b64 exec, exec, s[12:13]
	s_movk_i32 s12, 0x90
	v_mad_u64_u32 v[174:175], s[12:13], v23, s12, v[22:23]
	v_and_b32_e32 v15, 63, v17
	v_add_u32_e32 v21, 0, v174
	s_waitcnt vmcnt(1)
	ds_write_b128 v21, v[148:151] offset:13312
	v_lshlrev_b32_e32 v21, 2, v15
	s_mov_b64 s[12:13], -1
	s_cmp_gt_i32 s2, -1
	v_xor_b32_e32 v15, 0x80, v21
	s_waitcnt lgkmcnt(0)
	s_barrier
	s_cbranch_scc1 .LBB0_536
	v_xor_b32_e32 v48, 0x80, v21
	s_mov_b64 s[12:13], 0
.LBB0_536:
	s_andn2_b64 vcc, exec, s[12:13]
	v_lshlrev_b32_e32 v170, 3, v19
	s_cbranch_vccnz .LBB0_524
	s_and_b32 s87, s19, 0xffffffe0
	s_add_i32 s16, s16, s17
	s_add_i32 s87, s87, s3
	s_lshl_b32 s15, s2, 2
	s_lshl_b32 s12, s16, 17
	s_or_b32 s88, s87, 31
	s_add_i32 s2, s15, 4
	s_bfe_u32 s17, s16, 0x30004
	s_and_b32 s12, s12, 0xe00000
	s_add_u32 s12, s14, s12
	s_addc_u32 s13, 0, 0
	s_add_u32 s12, s93, s12
	v_readlane_b32 s14, v252, 61
	v_mov_b32_e32 v21, v1
	s_addc_u32 s13, s14, s13
	s_mulk_i32 s17, 0xc0
	v_and_b32_e32 v22, 31, v17
	v_and_b32_e32 v19, 19, v17
	v_lshlrev_b32_e32 v23, 1, v17
	v_lshrrev_b32_e32 v17, 1, v17
	v_lshl_add_u64 v[176:177], s[12:13], 0, v[20:21]
	s_add_u32 s12, s18, s17
	v_and_b32_e32 v23, 8, v23
	v_and_b32_e32 v17, 4, v17
	s_addc_u32 s13, 0, 0
	v_readlane_b32 s14, v252, 63
	v_or3_b32 v17, v19, v23, v17
	s_add_u32 s12, s14, s12
	v_readlane_b32 s14, v253, 1
	v_mul_u32_u24_e32 v169, 0xd0, v17
	v_mul_u32_u24_e32 v171, 0x90, v22
	v_mov_b32_e32 v17, v1
	v_mov_b32_e32 v19, v1
	v_add_u32_e32 v22, s87, v22
	s_addc_u32 s13, s14, s13
	v_mov_b32_e32 v32, v1
	v_mov_b32_e32 v33, v1
	v_sub_u32_e32 v173, v22, v170
	v_lshl_add_u64 v[178:179], s[12:13], 0, v[16:17]
	v_lshl_add_u64 v[180:181], s[12:13], 0, v[18:19]
	v_mov_b32_e32 v34, v1
	v_mov_b32_e32 v35, v1
	v_mov_b32_e32 v36, v1
	v_mov_b32_e32 v37, v1
	v_mov_b32_e32 v38, v1
	v_mov_b32_e32 v39, v1
	v_mov_b32_e32 v40, v1
	v_mov_b32_e32 v41, v1
	v_mov_b32_e32 v42, v1
	v_mov_b32_e32 v43, v1
	v_mov_b32_e32 v44, v1
	v_mov_b32_e32 v45, v1
	v_mov_b32_e32 v46, v1
	v_mov_b32_e32 v47, v1
	v_mov_b32_e32 v183, 0
	v_mov_b64_e32 v[16:17], v[32:33]
	s_mov_b64 s[0:1], s[90:91]
	s_mov_b32 s3, 1
	s_xor_b32 s90, s15, -4
	s_mov_b64 s[82:83], 0
	s_mov_b32 s91, 63
	v_mov_b64_e32 v[18:19], v[34:35]
	v_mov_b64_e32 v[20:21], v[36:37]
	v_mov_b64_e32 v[22:23], v[38:39]
	v_mov_b64_e32 v[24:25], v[40:41]
	v_mov_b64_e32 v[26:27], v[42:43]
	v_mov_b64_e32 v[28:29], v[44:45]
	v_mov_b64_e32 v[30:31], v[46:47]
	v_mov_b32_e32 v175, 0
	v_mov_b32_e32 v48, 0
	v_mov_b32_e32 v49, v183
	v_mov_b32_e32 v50, v183
	v_mov_b32_e32 v51, v183
	v_mov_b32_e32 v52, v183
	v_mov_b32_e32 v53, v183
	v_mov_b32_e32 v54, v183
	v_mov_b32_e32 v55, v183
	v_mov_b32_e32 v56, v183
	v_mov_b32_e32 v57, v183
	v_mov_b32_e32 v58, v183
	v_mov_b32_e32 v59, v183
	v_mov_b32_e32 v60, v183
	v_mov_b32_e32 v61, v183
	v_mov_b32_e32 v62, v183
	v_mov_b32_e32 v63, v183
	s_andn2_b64 vcc, exec, s[4:5]
	s_cbranch_vccnz .Lq_fallback
	s_movk_i32 s16, 0x5800
	s_waitcnt vmcnt(0)
	v_add_u32_e32 v209, s16, v14
	v_add_u32_e32 v210, s16, v174
	v_add_u32_e32 v211, s16, v172
	ds_write_b128 v209, v[214:217]
	ds_write_b128 v210, v[222:225] offset:13312
	s_and_saveexec_b64 s[14:15], s[10:11]
	ds_write_b128 v211, v[218:221]
	s_or_b64 exec, exec, s[14:15]
	s_mov_b64 s[14:15], 0x80
	v_lshl_add_u64 v[176:177], v[176:177], 0, s[14:15]
	v_lshl_add_u64 v[178:179], v[178:179], 0, s[96:97]
	v_lshl_add_u64 v[180:181], v[180:181], 0, s[96:97]
	s_and_saveexec_b64 s[14:15], s[10:11]
	global_load_dwordx4 v[144:147], v[180:181], off
	s_or_b64 exec, exec, s[14:15]
	global_load_dwordx4 v[140:143], v[178:179], off
	global_load_dwordx4 v[148:151], v[176:177], off
	s_mov_b64 s[14:15], 0x80
	v_lshl_add_u64 v[176:177], v[176:177], 0, s[14:15]
	v_lshl_add_u64 v[178:179], v[178:179], 0, s[96:97]
	v_lshl_add_u64 v[180:181], v[180:181], 0, s[96:97]
	s_lshr_b32 s20, s88, 6
	s_add_i32 s20, s20, 1
	s_min_i32 s20, s20, s2
	s_mov_b32 s3, 0
	s_waitcnt lgkmcnt(0)
	s_barrier
	v_add_u32_e32 v206, v169, v0
	ds_read_b128 v[96:99], v206
	ds_read_b128 v[104:107], v206 offset:6656
	ds_read_b128 v[100:103], v206 offset:32
	ds_read_b128 v[108:111], v206 offset:6688
	ds_read_b128 v[112:115], v206 offset:64
	ds_read_b128 v[120:123], v206 offset:6720
	ds_read_b128 v[116:119], v206 offset:96
	ds_read_b128 v[124:127], v206 offset:6752
	s_waitcnt lgkmcnt(4)
	v_mfma_f32_32x32x16_bf16 v[64:79], v[96:99], v[2:5], v[48:63]
	v_mfma_f32_32x32x16_bf16 v[80:95], v[104:107], v[2:5], v[48:63]
	v_mfma_f32_32x32x16_bf16 v[64:79], v[100:103], v[6:9], v[64:79]
	v_mfma_f32_32x32x16_bf16 v[80:95], v[108:111], v[6:9], v[80:95]
	ds_read_b128 v[96:99], v206 offset:128
	ds_read_b128 v[104:107], v206 offset:6784
	ds_read_b128 v[100:103], v206 offset:160
	ds_read_b128 v[108:111], v206 offset:6816
	s_waitcnt lgkmcnt(4)
	v_mfma_f32_32x32x16_bf16 v[64:79], v[112:115], v[10:13], v[64:79]
	v_mfma_f32_32x32x16_bf16 v[80:95], v[120:123], v[10:13], v[80:95]
	v_mfma_f32_32x32x16_bf16 v[64:79], v[116:119], v[128:131], v[64:79]
	v_mfma_f32_32x32x16_bf16 v[80:95], v[124:127], v[128:131], v[80:95]
	s_waitcnt lgkmcnt(0)
	v_mfma_f32_32x32x16_bf16 v[64:79], v[96:99], v[132:135], v[64:79]
	v_mfma_f32_32x32x16_bf16 v[80:95], v[104:107], v[132:135], v[80:95]
	v_mfma_f32_32x32x16_bf16 v[64:79], v[100:103], v[136:139], v[64:79]
	v_mfma_f32_32x32x16_bf16 v[80:95], v[108:111], v[136:139], v[80:95]

; #define UNPK8(v, f) do { f[0] = bflo(v.x); f[1] = bfhi(v.x); f[2] = bflo(v.y); f[3] = bfhi(v.y); f[4] = bflo(v.z); f[5] = bfhi(v.z); f[6] = bflo(v.w); f[7] = bfhi(v.w); } while (0)
; #define PACK8(v, f) do { v.x = pk2(f[0], f[1]); v.y = pk2(f[2], f[3]); v.z = pk2(f[4], f[5]); v.w = pk2(f[6], f[7]); } while (0)
; __device__ __forceinline__ float shfl_xor_l(float v, int o, int lane) { return __builtin_bit_cast(float, __builtin_amdgcn_ds_bpermute((lane ^ o) << 2, __builtin_bit_cast(int, v))); }
; template <int DQK, int DV, int FLAGS, int qp, int kp, int vts, int op> ...
;     ...
;     const int tid = tid_o, lane = tid & 63, r32 = lane & 31, hi = lane >> 5; const int wave = __builtin_amdgcn_readfirstlane(tid >> 6);
;     bf16x8 qr[ND0];
;     { const bf16* qrow = Q + (size_t)(32 * wave + r32) * qp + 8 * hi;
; #pragma unroll
;       for (int d0 = 0; d0 < ND0; ++d0) qr[d0] = *(const bf16x8*)(qrow + 16 * d0);
;       if (FLAGS & AF_QNORM) {
;           float ss = 0.f;
; #pragma unroll
;           for (int d0 = 0; d0 < ND0; ++d0) { const u32x4 v = __builtin_bit_cast(u32x4, qr[d0]); float f[8]; UNPK8(v, f);
; #pragma unroll
;               for (int i = 0; i < 8; ++i) ss += f[i] * f[i]; }
;           ss += shfl_xor_l(ss, 32, lane);
;           const float r = (1.0f / sqrtf(ss * (1.f / DQK) + EPS)) * qscale;
; #pragma unroll
;           for (int d0 = 0; d0 < ND0; ++d0) { const u32x4 v = __builtin_bit_cast(u32x4, qr[d0]); float f[8]; UNPK8(v, f);
; #pragma unroll
;               for (int i = 0; i < 8; ++i) f[i] *= r * qgain[16 * d0 + 8 * hi + i];
;               u32x4 o; PACK8(o, f); qr[d0] = __builtin_bit_cast(bf16x8, o); }
;       } }
.LBB0_1282:
	s_ashr_i32 s2, s36, 8
	s_ashr_i32 s3, s2, 31
	s_lshl_b32 s4, s36, 17
	s_and_b32 s6, s4, 0x7e0000
	s_lshl_b64 s[4:5], s[2:3], 23
	s_or_b32 s4, s4, s6
	s_lshl_b64 s[14:15], s[4:5], 1
	s_add_u32 s4, s74, s14
	s_addc_u32 s5, s75, s15
	s_lshl_b32 s6, s36, 1
	s_and_b32 s18, s6, 0x180
	s_lshl_b32 s37, s18, 1
	s_add_u32 s4, s4, s37
	s_addc_u32 s5, s5, 0
	s_and_b32 s6, s36, 0xffffff00
	s_ashr_i32 s7, s6, 31
	s_lshl_b64 s[6:7], s[6:7], 10
	s_add_u32 s6, s34, s6
	s_addc_u32 s7, s35, s7
	s_add_u32 s40, s6, s37
	s_addc_u32 s41, s7, 0
	s_lshl_b64 s[2:3], s[2:3], 9
	s_add_u32 s2, s2, s10
	s_load_dwordx2 s[6:7], s[82:83], 0xc8
	s_addc_u32 s3, s3, s11
	s_or_b32 s2, s2, s18
	s_lshl_b64 s[2:3], s[2:3], 9
	v_readlane_b32 s18, v252, 32
	v_readlane_b32 s19, v252, 33
	s_add_u32 s42, s18, s2
	s_addc_u32 s43, s19, s3
	v_mov_b32_e32 v58, v212
	s_waitcnt lgkmcnt(0)
	s_add_u32 s30, s6, s12
	s_addc_u32 s31, s7, s13
	v_readfirstlane_b32 s2, v58
	s_ashr_i32 s2, s2, 1
	v_bfe_u32 v204, v58, 5, 1
	v_mov_b32_e32 v0, s2
	s_movk_i32 s2, 0xffe0
	v_bfi_b32 v194, s2, v0, v58
	v_ashrrev_i32_e32 v195, 31, v194
	v_lshlrev_b64 v[2:3], 10, v[194:195]
	v_lshl_add_u64 v[2:3], s[4:5], 0, v[2:3]
	v_lshlrev_b32_e32 v0, 4, v204
	v_lshl_add_u64 v[14:15], v[2:3], 0, v[0:1]
	global_load_dwordx4 v[2:5], v[14:15], off offset:224
	global_load_dwordx4 v[6:9], v[14:15], off offset:192
	global_load_dwordx4 v[10:13], v[14:15], off offset:160
	global_load_dwordx4 v[46:49], v[14:15], off offset:128
	global_load_dwordx4 v[54:57], v[14:15], off offset:96
	global_load_dwordx4 v[60:63], v[14:15], off offset:64
	global_load_dwordx4 v[64:67], v[14:15], off offset:32
	global_load_dwordx4 v[68:71], v[14:15], off
	v_lshrrev_b32_e32 v228, 4, v58
	v_and_b32_e32 v229, 15, v58
	v_lshlrev_b32_e32 v229, 4, v229
	v_lshl_add_u32 v228, v228, 10, v229
	v_add_u32_e32 v229, 0x8000, v228
	v_lshrrev_b32_e32 v230, 3, v58
	v_and_b32_e32 v231, 7, v58
	v_lshlrev_b32_e32 v231, 4, v231
	v_lshl_or_b32 v230, v230, 9, v231
	v_add_u32_e32 v231, 0x8000, v230
	global_load_dwordx4 v[232:235], v228, s[40:41]
	global_load_dwordx4 v[236:239], v229, s[40:41]
	global_load_dwordx4 v[240:243], v230, s[42:43]
	global_load_dwordx4 v[244:247], v231, s[42:43]
	v_and_b32_e32 v59, 32, v58
	global_load_dwordx4 v[72:75], v59, s[30:31] offset:128
	v_and_b32_e32 v16, 63, v58
	v_lshlrev_b32_e32 v16, 2, v16
	v_xor_b32_e32 v205, 0x80, v16
	s_movk_i32 s4, 0xfd10
	s_waitcnt vmcnt(0)
	v_lshlrev_b32_e32 v20, 16, v2
	v_lshlrev_b32_e32 v28, 16, v6
	v_lshlrev_b32_e32 v36, 16, v10
	v_lshlrev_b32_e32 v38, 16, v49
	v_and_b32_e32 v39, 0xffff0000, v49
	v_lshlrev_b32_e32 v124, 16, v60
	v_lshlrev_b32_e32 v136, 16, v64
	v_lshlrev_b32_e32 v150, 16, v68
	v_and_b32_e32 v151, 0xffff0000, v68
	v_lshlrev_b32_e32 v146, 16, v69
	v_and_b32_e32 v147, 0xffff0000, v69
	v_pk_mul_f32 v[68:69], v[150:151], v[150:151]
	v_pk_mul_f32 v[148:149], v[146:147], v[146:147]
	v_add_f32_e32 v68, v68, v69
	v_lshlrev_b32_e32 v144, 16, v70
	v_and_b32_e32 v145, 0xffff0000, v70
	v_add_f32_e32 v68, v148, v68
	v_lshlrev_b32_e32 v140, 16, v71
	v_and_b32_e32 v141, 0xffff0000, v71
	v_pk_mul_f32 v[70:71], v[144:145], v[144:145]
	v_add_f32_e32 v68, v149, v68
	v_add_f32_e32 v68, v70, v68
	v_pk_mul_f32 v[142:143], v[140:141], v[140:141]
	v_add_f32_e32 v68, v71, v68
	v_and_b32_e32 v137, 0xffff0000, v64
	v_add_f32_e32 v68, v142, v68
	v_pk_mul_f32 v[138:139], v[136:137], v[136:137]
	v_add_f32_e32 v68, v143, v68
	v_lshlrev_b32_e32 v132, 16, v65
	v_and_b32_e32 v133, 0xffff0000, v65
	v_add_f32_e32 v68, v138, v68
	v_pk_mul_f32 v[134:135], v[132:133], v[132:133]
	v_add_f32_e32 v68, v139, v68
	v_lshlrev_b32_e32 v128, 16, v66
	v_and_b32_e32 v129, 0xffff0000, v66
	v_add_f32_e32 v68, v134, v68
	v_pk_mul_f32 v[130:131], v[128:129], v[128:129]
	v_add_f32_e32 v68, v135, v68
	v_lshlrev_b32_e32 v120, 16, v67
	v_and_b32_e32 v121, 0xffff0000, v67
	v_add_f32_e32 v68, v130, v68
	v_pk_mul_f32 v[126:127], v[120:121], v[120:121]
	v_add_f32_e32 v68, v131, v68
	v_and_b32_e32 v125, 0xffff0000, v60
	v_add_f32_e32 v68, v126, v68
	v_pk_mul_f32 v[118:119], v[124:125], v[124:125]
	v_add_f32_e32 v68, v127, v68
	v_lshlrev_b32_e32 v122, 16, v61
	v_and_b32_e32 v123, 0xffff0000, v61
	v_add_f32_e32 v68, v118, v68
	v_pk_mul_f32 v[116:117], v[122:123], v[122:123]
	v_add_f32_e32 v68, v119, v68
	v_lshlrev_b32_e32 v40, 16, v48
	v_and_b32_e32 v41, 0xffff0000, v48
	v_lshlrev_b32_e32 v42, 16, v47
	v_and_b32_e32 v43, 0xffff0000, v47
	v_lshlrev_b32_e32 v44, 16, v46
	v_and_b32_e32 v45, 0xffff0000, v46
	v_lshlrev_b32_e32 v46, 16, v57
	v_and_b32_e32 v47, 0xffff0000, v57
	v_lshlrev_b32_e32 v48, 16, v56
	v_and_b32_e32 v49, 0xffff0000, v56
	v_lshlrev_b32_e32 v56, 16, v62
	v_and_b32_e32 v57, 0xffff0000, v62
	v_add_f32_e32 v68, v116, v68
	v_pk_mul_f32 v[114:115], v[56:57], v[56:57]
	v_add_f32_e32 v68, v117, v68
	v_lshlrev_b32_e32 v50, 16, v55
	v_and_b32_e32 v51, 0xffff0000, v55
	v_lshlrev_b32_e32 v52, 16, v54
	v_and_b32_e32 v53, 0xffff0000, v54
	v_lshlrev_b32_e32 v54, 16, v63
	v_and_b32_e32 v55, 0xffff0000, v63
	v_add_f32_e32 v68, v114, v68
	v_pk_mul_f32 v[112:113], v[54:55], v[54:55]
	v_add_f32_e32 v68, v115, v68
	v_add_f32_e32 v68, v112, v68
	v_pk_mul_f32 v[110:111], v[52:53], v[52:53]
	global_load_dwordx4 v[60:63], v59, s[30:31] offset:80
	global_load_dwordx4 v[76:79], v59, s[30:31] offset:64
	global_load_dwordx4 v[64:67], v59, s[30:31] offset:16
	global_load_dwordx4 v[80:83], v59, s[30:31]
	v_add_f32_e32 v68, v113, v68
	v_add_f32_e32 v68, v110, v68
	v_pk_mul_f32 v[108:109], v[50:51], v[50:51]
	v_add_f32_e32 v68, v111, v68
	v_add_f32_e32 v68, v108, v68
	v_pk_mul_f32 v[106:107], v[48:49], v[48:49]
	v_add_f32_e32 v68, v109, v68
	v_add_f32_e32 v68, v106, v68
; #define UNPK8(v, f) do { f[0] = bflo(v.x); f[1] = bfhi(v.x); f[2] = bflo(v.y); f[3] = bfhi(v.y); f[4] = bflo(v.z); f[5] = bfhi(v.z); f[6] = bflo(v.w); f[7] = bfhi(v.w); } while (0)
; #define PACK8(v, f) do { v.x = pk2(f[0], f[1]); v.y = pk2(f[2], f[3]); v.z = pk2(f[4], f[5]); v.w = pk2(f[6], f[7]); } while (0)
; __device__ __forceinline__ float shfl_xor_l(float v, int o, int lane) { return __builtin_bit_cast(float, __builtin_amdgcn_ds_bpermute((lane ^ o) << 2, __builtin_bit_cast(int, v))); }
; template <int DQK, int DV, int FLAGS, int qp, int kp, int vts, int op> ...
;     ...
;       if (FLAGS & AF_QNORM) {
;           float ss = 0.f;
; #pragma unroll
;           for (int d0 = 0; d0 < ND0; ++d0) { const u32x4 v = __builtin_bit_cast(u32x4, qr[d0]); float f[8]; UNPK8(v, f);
; #pragma unroll
;               for (int i = 0; i < 8; ++i) ss += f[i] * f[i]; }
;           ss += shfl_xor_l(ss, 32, lane);
;           const float r = (1.0f / sqrtf(ss * (1.f / DQK) + EPS)) * qscale;
; #pragma unroll
;           for (int d0 = 0; d0 < ND0; ++d0) { const u32x4 v = __builtin_bit_cast(u32x4, qr[d0]); float f[8]; UNPK8(v, f);
; #pragma unroll
;               for (int i = 0; i < 8; ++i) f[i] *= r * qgain[16 * d0 + 8 * hi + i];
;               u32x4 o; PACK8(o, f); qr[d0] = __builtin_bit_cast(bf16x8, o); }
	v_pk_mul_f32 v[104:105], v[46:47], v[46:47]
	v_add_f32_e32 v68, v107, v68
	v_add_f32_e32 v68, v104, v68
	v_pk_mul_f32 v[102:103], v[44:45], v[44:45]
	v_add_f32_e32 v68, v105, v68
	v_add_f32_e32 v68, v102, v68
	v_pk_mul_f32 v[100:101], v[42:43], v[42:43]
	v_add_f32_e32 v68, v103, v68
	v_add_f32_e32 v68, v100, v68
	v_pk_mul_f32 v[98:99], v[40:41], v[40:41]
	v_add_f32_e32 v68, v101, v68
	v_add_f32_e32 v68, v98, v68
	v_pk_mul_f32 v[96:97], v[38:39], v[38:39]
	v_add_f32_e32 v68, v99, v68
	v_and_b32_e32 v37, 0xffff0000, v10
	v_add_f32_e32 v68, v96, v68
	v_pk_mul_f32 v[94:95], v[36:37], v[36:37]
	v_add_f32_e32 v68, v97, v68
	v_lshlrev_b32_e32 v34, 16, v11
	v_and_b32_e32 v35, 0xffff0000, v11
	v_add_f32_e32 v68, v94, v68
	v_pk_mul_f32 v[92:93], v[34:35], v[34:35]
	v_add_f32_e32 v68, v95, v68
	v_lshlrev_b32_e32 v32, 16, v12
	v_and_b32_e32 v33, 0xffff0000, v12
	v_add_f32_e32 v68, v92, v68
	v_pk_mul_f32 v[90:91], v[32:33], v[32:33]
	v_add_f32_e32 v68, v93, v68
	v_lshlrev_b32_e32 v30, 16, v13
	v_and_b32_e32 v31, 0xffff0000, v13
	v_add_f32_e32 v68, v90, v68
	v_pk_mul_f32 v[88:89], v[30:31], v[30:31]
	v_add_f32_e32 v68, v91, v68
	v_and_b32_e32 v29, 0xffff0000, v6
	v_add_f32_e32 v68, v88, v68
	v_pk_mul_f32 v[86:87], v[28:29], v[28:29]
	v_add_f32_e32 v68, v89, v68
	v_lshlrev_b32_e32 v26, 16, v7
	v_and_b32_e32 v27, 0xffff0000, v7
	v_add_f32_e32 v68, v86, v68
	v_pk_mul_f32 v[84:85], v[26:27], v[26:27]
	v_add_f32_e32 v68, v87, v68
	v_lshlrev_b32_e32 v24, 16, v8
	v_and_b32_e32 v25, 0xffff0000, v8
	v_add_f32_e32 v68, v84, v68
	v_pk_mul_f32 v[12:13], v[24:25], v[24:25]
	v_add_f32_e32 v68, v85, v68
	v_lshlrev_b32_e32 v22, 16, v9
	v_and_b32_e32 v23, 0xffff0000, v9
	v_add_f32_e32 v12, v12, v68
	v_pk_mul_f32 v[10:11], v[22:23], v[22:23]
	v_add_f32_e32 v12, v13, v12
	v_and_b32_e32 v21, 0xffff0000, v2
	v_add_f32_e32 v10, v10, v12
	v_pk_mul_f32 v[8:9], v[20:21], v[20:21]
	v_add_f32_e32 v10, v11, v10
	v_lshlrev_b32_e32 v18, 16, v3
	v_and_b32_e32 v19, 0xffff0000, v3
	v_add_f32_e32 v8, v8, v10
	v_pk_mul_f32 v[6:7], v[18:19], v[18:19]
	v_add_f32_e32 v8, v9, v8
	v_lshlrev_b32_e32 v16, 16, v4
	v_and_b32_e32 v17, 0xffff0000, v4
	v_add_f32_e32 v6, v6, v8
	v_lshlrev_b32_e32 v14, 16, v5
	v_and_b32_e32 v15, 0xffff0000, v5
	v_pk_mul_f32 v[4:5], v[16:17], v[16:17]
	v_add_f32_e32 v6, v7, v6
	v_add_f32_e32 v4, v4, v6
	v_pk_mul_f32 v[2:3], v[14:15], v[14:15]
	v_add_f32_e32 v4, v5, v4
	v_add_f32_e32 v2, v2, v4
	v_add_f32_e32 v10, v3, v2
	ds_bpermute_b32 v11, v205, v10
	global_load_dwordx4 v[68:71], v59, s[30:31] offset:144
	global_load_dwordx4 v[2:5], v59, s[30:31] offset:464
	global_load_dwordx4 v[6:9], v59, s[30:31] offset:448
	v_and_b32_e32 v113, 31, v58
	s_waitcnt lgkmcnt(0)
	v_add_f32_e32 v10, v10, v11
	v_fmamk_f32 v10, v10, 0x3c000000, v214
	v_mul_f32_e32 v11, 0x4f800000, v10
	v_cmp_gt_f32_e32 vcc, s33, v10
	s_nop 1
	v_cndmask_b32_e32 v96, v10, v11, vcc
	v_sqrt_f32_e32 v97, v96
	global_load_dwordx4 v[10:13], v59, s[30:31] offset:400
	global_load_dwordx4 v[84:87], v59, s[30:31] offset:384
	global_load_dwordx4 v[88:91], v59, s[30:31] offset:208
	global_load_dwordx4 v[92:95], v59, s[30:31] offset:192
	v_add_u32_e32 v98, -1, v97
	v_fma_f32 v99, -v98, v97, v96
	v_cmp_ge_f32_e64 s[6:7], 0, v99
	v_add_u32_e32 v99, 1, v97
	s_nop 0
	v_cndmask_b32_e64 v98, v97, v98, s[6:7]
	v_fma_f32 v97, -v99, v97, v96
	v_cmp_lt_f32_e64 s[6:7], 0, v97
	s_nop 1
	v_cndmask_b32_e64 v97, v98, v99, s[6:7]
	v_mul_f32_e32 v98, 0x37800000, v97
	v_cndmask_b32_e32 v97, v97, v98, vcc
	v_cmp_class_f32_e32 vcc, v96, v215
	s_nop 1
	v_cndmask_b32_e32 v112, v97, v96, vcc
	v_div_scale_f32 v114, s[2:3], v112, v112, 1.0
	v_rcp_f32_e32 v115, v114
	global_load_dwordx4 v[96:99], v59, s[30:31] offset:336
	global_load_dwordx4 v[100:103], v59, s[30:31] offset:320
	global_load_dwordx4 v[104:107], v59, s[30:31] offset:272
	global_load_dwordx4 v[108:111], v59, s[30:31] offset:256
	v_fma_f32 v59, -v114, v115, 1.0
	v_fmac_f32_e32 v115, v59, v115
	v_div_scale_f32 v59, vcc, 1.0, v112, 1.0
	v_mul_f32_e32 v116, v59, v115
	v_fma_f32 v117, -v114, v116, v59
	v_fmac_f32_e32 v116, v117, v115
	v_fma_f32 v59, -v114, v116, v59
	v_div_fmas_f32 v59, v59, v115, v116
	v_div_fixup_f32 v59, v59, v112, 1.0
	v_mul_f32_e32 v112, 0x3e0293ee, v59
	v_ashrrev_i32_e32 v59, 31, v58
	v_lshrrev_b32_e32 v59, 28, v59
	v_add_u32_e32 v59, v58, v59
	s_waitcnt vmcnt(14)
	v_pk_mul_f32 v[60:61], v[60:61], v[112:113] op_sel_hi:[1,0]
	v_ashrrev_i32_e32 v143, 4, v59
	v_and_b32_e32 v59, 0xffffff0, v59
	s_waitcnt vmcnt(11)
	v_pk_mul_f32 v[80:81], v[80:81], v[112:113] op_sel_hi:[1,0]
	v_pk_mul_f32 v[60:61], v[60:61], v[128:129]
	v_pk_mul_f32 v[62:63], v[62:63], v[112:113] op_sel_hi:[1,0]
	v_sub_u32_e32 v59, v58, v59
	v_pk_mul_f32 v[80:81], v[80:81], v[150:151]
	v_pk_mul_f32 v[82:83], v[82:83], v[112:113] op_sel_hi:[1,0]
	v_pk_mul_f32 v[62:63], v[62:63], v[120:121]
	v_cvt_pk_bf16_f32 v120, v60, v61
	v_pk_mul_f32 v[60:61], v[72:73], v[112:113] op_sel_hi:[1,0]
	v_lshlrev_b32_e32 v59, 4, v59
	v_pk_mul_f32 v[82:83], v[82:83], v[146:147]
	v_cvt_pk_bf16_f32 v114, v80, v81
	v_pk_mul_f32 v[80:81], v[60:61], v[124:125]
	v_pk_mul_f32 v[60:61], v[74:75], v[112:113] op_sel_hi:[1,0]
	v_lshl_add_u32 v196, v143, 10, v59
	v_add_u32_e32 v59, 0x200, v58
	v_cvt_pk_bf16_f32 v115, v82, v83
	v_pk_mul_f32 v[82:83], v[60:61], v[122:123]
	v_ashrrev_i32_e32 v60, 31, v59
	v_lshrrev_b32_e32 v60, 28, v60
	v_pk_mul_f32 v[64:65], v[64:65], v[112:113] op_sel_hi:[1,0]
	v_add_u32_e32 v60, v59, v60
	v_pk_mul_f32 v[64:65], v[64:65], v[144:145]
	v_pk_mul_f32 v[66:67], v[66:67], v[112:113] op_sel_hi:[1,0]
	v_ashrrev_i32_e32 v145, 4, v60
	v_and_b32_e32 v60, 0xffffff0, v60
	v_pk_mul_f32 v[66:67], v[66:67], v[140:141]
	v_sub_u32_e32 v60, v59, v60
	v_lshlrev_b32_e32 v72, 4, v58
	v_cvt_pk_bf16_f32 v116, v64, v65
	v_cvt_pk_bf16_f32 v117, v66, v67
	v_pk_mul_f32 v[64:65], v[76:77], v[112:113] op_sel_hi:[1,0]
	v_pk_mul_f32 v[66:67], v[78:79], v[112:113] op_sel_hi:[1,0]
	v_lshlrev_b32_e32 v60, 4, v60
	v_and_b32_e32 v144, 0x70, v72
	v_ashrrev_i32_e32 v146, 3, v58
	v_ashrrev_i32_e32 v59, 3, v59
	v_pk_mul_f32 v[64:65], v[64:65], v[136:137]
	v_pk_mul_f32 v[66:67], v[66:67], v[132:133]
	v_lshl_add_u32 v198, v145, 10, v60
	v_lshl_or_b32 v200, v146, 9, v144
	v_lshl_or_b32 v202, v59, 9, v144
	v_cvt_pk_bf16_f32 v118, v64, v65
	v_cvt_pk_bf16_f32 v119, v66, v67
	v_cvt_pk_bf16_f32 v121, v62, v63
	s_waitcnt vmcnt(10)
; template <int DQK, int DV, int FLAGS, int qp, int kp, int vts, int op> ...
;     ...
;           for (int d0 = 0; d0 < ND0; ++d0) { const u32x4 v = __builtin_bit_cast(u32x4, qr[d0]); float f[8]; UNPK8(v, f);
; #pragma unroll
;               for (int i = 0; i < 8; ++i) f[i] *= r * qgain[16 * d0 + 8 * hi + i];
;               u32x4 o; PACK8(o, f); qr[d0] = __builtin_bit_cast(bf16x8, o); }
;       } }
;     const int qpos = q0 + 32 * wave + r32, qmin_w = q0 + 32 * wave, qmax_w = qmin_w + 31;
;     f32x16 o[NDB];
; #pragma unroll
;     for (int d = 0; d < NDB; ++d)
; #pragma unroll
;         for (int r = 0; r < 16; ++r) o[d][r] = 0.f;
;     float m = (FLAGS & AF_ROBUST) ? -1e30f : 0.f, l = 0.f;
;     f32x16 negm;
; #pragma unroll
;     for (int r = 0; r < 16; ++r) negm[r] = 0.f;
;     u32x4 kreg[KPT], vreg[VPT];
;     unsigned kgo[KPT], vgo[VPT], klo[KPT], vlo[VPT];
; #pragma unroll
;     for (int i = 0; i < KPT; ++i) { const int c = tid + i * NTHREADS; const int row = c / KC, cc = c % KC; kgo[i] = (unsigned)(row * kp + cc * 8) * 2u; klo[i] = (unsigned)(row * KROW + cc * 16); }
; #pragma unroll
;     for (int i = 0; i < VPT; ++i) { const int c = tid + i * NTHREADS; const int d = c >> 3, cc = c & 7; vgo[i] = (unsigned)(d * vts + cc * 8) * 2u; vlo[i] = (unsigned)(KT_BYTES + d * VROW + cc * 16); }
;     ...
;     ATT_GLOAD((FLAGS & AF_REV) ? kt_hi - 1 : kt_lo); ATT_LSTORE(0);
;     __syncthreads();
;     ...
;             const LAS unsigned char* kb = lds + cur * BUF + prow * KROW + 16 * hi;
;             const LAS unsigned char* vb = lds + cur * BUF + KT_BYTES + r32 * VROW + 16 * hi;
;             f32x16 p0, p1;
;             bf16x8 kf[2][4];
; #pragma unroll
;             for (int i = 0; i < 2; ++i) { kf[0][2 * i] = *(const LAS bf16x8*)(kb + i * 32); kf[0][2 * i + 1] = *(const LAS bf16x8*)(kb + 32 * KROW + i * 32); }
;             const int nrel = qpos - kv0 - 8 * hi;
;             if (FLAGS & AF_ALIBI) { const float ab = -slope2 * (float)nrel - ((FLAGS & AF_ROBUST) ? 0.f : m);
; #pragma unroll
;                 for (int r = 0; r < 16; ++r) { const float c = (float)(16 * (r >> 3) + (r & 7)); p0[r] = __builtin_fmaf(slope2, c, ab); p1[r] = __builtin_fmaf(slope2, c + 32.f, ab); }
;             } else if (FLAGS & AF_ROBUST) {
; #pragma unroll
;                 for (int r = 0; r < 16; ++r) { p0[r] = 0.f; p1[r] = 0.f; }
;             } else { p0 = negm; p1 = negm; }
	v_pk_mul_f32 v[68:69], v[68:69], v[112:113] op_sel_hi:[1,0]
	s_waitcnt vmcnt(7)
	v_pk_mul_f32 v[10:11], v[10:11], v[112:113] op_sel_hi:[1,0]
	v_pk_mul_f32 v[56:57], v[68:69], v[56:57]
	v_pk_mul_f32 v[68:69], v[70:71], v[112:113] op_sel_hi:[1,0]
	v_pk_mul_f32 v[10:11], v[10:11], v[24:25]
	v_pk_mul_f32 v[54:55], v[68:69], v[54:55]
	v_pk_mul_f32 v[12:13], v[12:13], v[112:113] op_sel_hi:[1,0]
	v_cvt_pk_bf16_f32 v125, v54, v55
	s_waitcnt vmcnt(4)
	v_pk_mul_f32 v[54:55], v[92:93], v[112:113] op_sel_hi:[1,0]
	v_pk_mul_f32 v[2:3], v[2:3], v[112:113] op_sel_hi:[1,0]
	v_pk_mul_f32 v[52:53], v[54:55], v[52:53]
	v_pk_mul_f32 v[54:55], v[94:95], v[112:113] op_sel_hi:[1,0]
	v_pk_mul_f32 v[12:13], v[12:13], v[22:23]
	v_pk_mul_f32 v[50:51], v[54:55], v[50:51]
	v_pk_mul_f32 v[54:55], v[88:89], v[112:113] op_sel_hi:[1,0]
	v_cvt_pk_bf16_f32 v140, v10, v11
	v_pk_mul_f32 v[48:49], v[54:55], v[48:49]
	v_pk_mul_f32 v[54:55], v[90:91], v[112:113] op_sel_hi:[1,0]
	v_pk_mul_f32 v[10:11], v[2:3], v[16:17]
	v_pk_mul_f32 v[46:47], v[54:55], v[46:47]
	v_pk_mul_f32 v[2:3], v[4:5], v[112:113] op_sel_hi:[1,0]
	v_cvt_pk_bf16_f32 v129, v46, v47
	s_waitcnt vmcnt(0)
	v_pk_mul_f32 v[46:47], v[108:109], v[112:113] op_sel_hi:[1,0]
	v_cvt_pk_bf16_f32 v141, v12, v13
	v_pk_mul_f32 v[44:45], v[46:47], v[44:45]
	v_pk_mul_f32 v[46:47], v[110:111], v[112:113] op_sel_hi:[1,0]
	v_pk_mul_f32 v[12:13], v[2:3], v[14:15]
	v_mad_u64_u32 v[2:3], s[2:3], v143, s4, v[196:197]
	v_pk_mul_f32 v[42:43], v[46:47], v[42:43]
	v_pk_mul_f32 v[46:47], v[104:105], v[112:113] op_sel_hi:[1,0]
	v_add_u32_e32 v207, 0, v2
	v_mad_u64_u32 v[2:3], s[2:3], v146, s20, v[144:145]
	v_pk_mul_f32 v[40:41], v[46:47], v[40:41]
	v_pk_mul_f32 v[46:47], v[106:107], v[112:113] op_sel_hi:[1,0]
	v_mad_u64_u32 v[4:5], s[2:3], v145, s4, v[198:199]
	v_add_u32_e32 v209, 0, v2
	v_mad_u64_u32 v[2:3], s[2:3], v59, s20, v[144:145]
	v_pk_mul_f32 v[38:39], v[46:47], v[38:39]
	v_add_u32_e32 v208, 0, v4
	v_lshlrev_b32_e32 v3, 1, v58
	v_lshrrev_b32_e32 v4, 1, v58
	v_cvt_pk_bf16_f32 v133, v38, v39
	v_pk_mul_f32 v[38:39], v[100:101], v[112:113] op_sel_hi:[1,0]
	v_add_u32_e32 v210, 0, v2
	v_and_b32_e32 v2, 19, v58
	v_and_b32_e32 v3, 8, v3
	v_and_b32_e32 v4, 4, v4
	v_pk_mul_f32 v[36:37], v[38:39], v[36:37]
	v_pk_mul_f32 v[38:39], v[102:103], v[112:113] op_sel_hi:[1,0]
	v_or3_b32 v2, v3, v2, v4
	s_movk_i32 s2, 0x110
	v_pk_mul_f32 v[34:35], v[38:39], v[34:35]
	v_pk_mul_f32 v[38:39], v[96:97], v[112:113] op_sel_hi:[1,0]
	v_mad_u32_u24 v2, v2, s2, 0
	v_pk_mul_f32 v[32:33], v[38:39], v[32:33]
	v_pk_mul_f32 v[38:39], v[98:99], v[112:113] op_sel_hi:[1,0]
	v_pk_mul_f32 v[6:7], v[6:7], v[112:113] op_sel_hi:[1,0]
	v_pk_mul_f32 v[8:9], v[8:9], v[112:113] op_sel_hi:[1,0]
	v_add_u32_e32 v206, v2, v0
	v_cvt_pk_bf16_f32 v132, v40, v41
	v_pk_mul_f32 v[30:31], v[38:39], v[30:31]
	v_cvt_pk_bf16_f32 v134, v36, v37
	v_cvt_pk_bf16_f32 v135, v34, v35
	v_pk_mul_f32 v[6:7], v[6:7], v[20:21]
	v_pk_mul_f32 v[8:9], v[8:9], v[18:19]
	v_cvt_pk_bf16_f32 v137, v30, v31
	v_pk_mul_f32 v[30:31], v[84:85], v[112:113] op_sel_hi:[1,0]
	v_cvt_pk_bf16_f32 v122, v80, v81
	v_pk_mul_f32 v[28:29], v[30:31], v[28:29]
	v_pk_mul_f32 v[30:31], v[86:87], v[112:113] op_sel_hi:[1,0]
	v_cvt_pk_bf16_f32 v123, v82, v83
	v_pk_mul_f32 v[26:27], v[30:31], v[26:27]
	s_waitcnt vmcnt(3)
	ds_write_b128 v207, v[232:235]
	s_waitcnt vmcnt(2)
	ds_write_b128 v208, v[236:239]
	s_waitcnt vmcnt(1)
	ds_write_b128 v209, v[240:243] offset:17408
	s_waitcnt vmcnt(0)
	ds_write_b128 v210, v[244:247] offset:17408
	s_waitcnt lgkmcnt(0)
	s_barrier
	ds_read_b128 v[2:5], v206
	ds_read_b128 v[34:37], v206 offset:32
	ds_read_b128 v[18:21], v206 offset:8704
	ds_read_b128 v[38:41], v206 offset:8736
	v_cvt_pk_bf16_f32 v124, v56, v57
	v_cvt_pk_bf16_f32 v126, v52, v53
	v_cvt_pk_bf16_f32 v127, v50, v51
	v_cvt_pk_bf16_f32 v128, v48, v49
	v_cvt_pk_bf16_f32 v130, v44, v45
	v_cvt_pk_bf16_f32 v131, v42, v43
	v_cvt_pk_bf16_f32 v136, v32, v33
	v_cvt_pk_bf16_f32 v138, v28, v29
	v_cvt_pk_bf16_f32 v139, v26, v27
	v_cvt_pk_bf16_f32 v142, v6, v7
	v_cvt_pk_bf16_f32 v143, v8, v9
	v_cvt_pk_bf16_f32 v144, v10, v11
	v_cvt_pk_bf16_f32 v145, v12, v13
	v_mul_u32_u24_e32 v54, 0x90, v113
	s_waitcnt lgkmcnt(3)
	v_mfma_f32_32x32x16_bf16 v[2:17], v[2:5], v[114:117], 0
	s_waitcnt lgkmcnt(1)
	v_mfma_f32_32x32x16_bf16 v[18:33], v[18:21], v[114:117], 0
	v_mfma_f32_32x32x16_bf16 v[2:17], v[34:37], v[118:121], v[2:17]
	ds_read_b128 v[34:37], v206 offset:64
	ds_read_b128 v[42:45], v206 offset:96
	ds_read_b128 v[46:49], v206 offset:8768
	ds_read_b128 v[50:53], v206 offset:8800
	s_waitcnt lgkmcnt(4)
	v_mfma_f32_32x32x16_bf16 v[18:33], v[38:41], v[118:121], v[18:33]
	s_waitcnt lgkmcnt(3)
	v_mfma_f32_32x32x16_bf16 v[2:17], v[34:37], v[122:125], v[2:17]
	s_waitcnt lgkmcnt(1)
	v_mfma_f32_32x32x16_bf16 v[18:33], v[46:49], v[122:125], v[18:33]
	v_mfma_f32_32x32x16_bf16 v[2:17], v[42:45], v[126:129], v[2:17]
	ds_read_b128 v[34:37], v206 offset:128
	ds_read_b128 v[38:41], v206 offset:160
	ds_read_b128 v[42:45], v206 offset:8832
	ds_read_b128 v[46:49], v206 offset:8864
	s_waitcnt lgkmcnt(4)
	v_mfma_f32_32x32x16_bf16 v[18:33], v[50:53], v[126:129], v[18:33]
	s_waitcnt lgkmcnt(3)
	v_mfma_f32_32x32x16_bf16 v[2:17], v[34:37], v[130:133], v[2:17]
	s_waitcnt lgkmcnt(1)
	v_mfma_f32_32x32x16_bf16 v[18:33], v[42:45], v[130:133], v[18:33]
	v_mfma_f32_32x32x16_bf16 v[2:17], v[38:41], v[134:137], v[2:17]
	ds_read_b128 v[34:37], v206 offset:192
	ds_read_b128 v[38:41], v206 offset:224
	ds_read_b128 v[42:45], v206 offset:8896
	ds_read_b128 v[50:53], v206 offset:8928
	s_waitcnt lgkmcnt(4)
	v_mfma_f32_32x32x16_bf16 v[18:33], v[46:49], v[134:137], v[18:33]
	s_waitcnt lgkmcnt(3)
; template <int DQK, int DV, int FLAGS, int qp, int kp, int vts, int op> ...
;     ...
;             if (more) ATT_GLOAD((FLAGS & AF_REV) ? t - 1 : t + 1);
;             bf16x8 vf[2][4];
; #pragma unroll
;             for (int ks = 0; ks < 4; ++ks) vf[0][ks] = *(const LAS bf16x8*)(vb + ks * 32);
;             __builtin_amdgcn_sched_barrier(0);
;             bool need_mask = false;
;             if (FLAGS & AF_CAUSAL) need_mask = need_mask || (kv0 + 63 > qmin_w);
;             if (FLAGS & AF_WINDOW) need_mask = need_mask || (kv0 < qmax_w - (SWA_W - 1));
;             if (need_mask) {
; #pragma unroll
;                 for (int r = 0; r < 16; ++r) { const int c = 16 * (r >> 3) + (r & 7);
;                     bool m0 = false, m1 = false;
;                     if (FLAGS & AF_CAUSAL) { m0 = m0 || (c > nrel); m1 = m1 || (c + 32 > nrel); }
;                     if (FLAGS & AF_WINDOW) { m0 = m0 || (c <= nrel - SWA_W); m1 = m1 || (c + 32 <= nrel - SWA_W); }
;                     if (m0) p0[r] = -INFINITY; if (m1) p1[r] = -INFINITY; }
;             }
;             float mx = 0.f;
;             if ((FLAGS & AF_ROBUST) || !started || !skipmax) {
;               float a = MX3(p0[0], p0[1], p1[0]), b = MX3(p0[2], p0[3], p1[1]); a = MX3(a, p1[2], p1[3]);
; #pragma unroll
;               for (int r = 4; r < 16; r += 4) { a = MX3(a, p0[r], p0[r + 1]); b = MX3(b, p0[r + 2], p0[r + 3]); a = MX3(a, p1[r], p1[r + 1]); b = MX3(b, p1[r + 2], p1[r + 3]); }
;               mx = __builtin_fmaxf(a, b);
;               if ((FLAGS & AF_ROBUST) || !started) mx = __builtin_fmaxf(mx, shfl_xor_l(mx, 32, lane)); }
;             if (FLAGS & AF_ROBUST) {
;                 if (__any(mx > m + 8.0f)) {
;                     const float mn = fmaxf(m, mx), alpha = __builtin_amdgcn_exp2f(m - mn);
;                     l *= alpha; m = mn;
; #pragma unroll
;                     for (int d = 0; d < NDB; ++d)
; #pragma unroll
;                         for (int r = 0; r < 16; ++r) o[d][r] *= alpha;
;                 }
; #pragma unroll
;                 for (int r = 0; r < 16; ++r) { p0[r] -= m; p1[r] -= m; }
;             } else {
;                 if (!started) {
;                     started = true;
;                     m = mx;
; #pragma unroll
;                     for (int r = 0; r < 16; ++r) { p0[r] -= mx; p1[r] -= mx; }
;                     if (!(FLAGS & AF_ALIBI)) {
; #pragma unroll
	v_mfma_f32_32x32x16_bf16 v[2:17], v[34:37], v[138:141], v[2:17]
	s_waitcnt lgkmcnt(1)
	v_mfma_f32_32x32x16_bf16 v[18:33], v[42:45], v[138:141], v[18:33]
	v_mfma_f32_32x32x16_bf16 v[2:17], v[38:41], v[142:145], v[2:17]
	s_waitcnt lgkmcnt(0)
	v_mfma_f32_32x32x16_bf16 v[18:33], v[50:53], v[142:145], v[18:33]
	s_add_u32 s2, s40, 0x10000
	s_addc_u32 s3, s41, 0
	global_load_dwordx4 v[82:85], v196, s[2:3]
	global_load_dwordx4 v[86:89], v198, s[2:3]
	global_load_dwordx4 v[90:93], v200, s[42:43] offset:128
	global_load_dwordx4 v[94:97], v202, s[42:43] offset:128
	v_add3_u32 v0, 0, v54, v0
	ds_read_b128 v[34:37], v0 offset:17408
	ds_read_b128 v[38:41], v0 offset:17440
	ds_read_b128 v[42:45], v0 offset:17472
	ds_read_b128 v[46:49], v0 offset:17504
	v_max_f32_e32 v50, v3, v3
	v_max_f32_e32 v51, v2, v2
	v_max_f32_e32 v50, v51, v50
	v_max3_f32 v50, v50, v18, v20
	v_max3_f32 v51, v4, v5, v19
	v_max3_f32 v50, v50, v21, v6
	v_max3_f32 v51, v51, v8, v9
	v_max3_f32 v50, v50, v7, v22
	v_max3_f32 v51, v51, v24, v25
	v_max3_f32 v50, v50, v23, v10
	v_max3_f32 v51, v51, v12, v13
	v_max3_f32 v50, v50, v11, v26
	v_max3_f32 v51, v51, v28, v29
	v_max3_f32 v50, v50, v27, v14
	v_max3_f32 v51, v51, v16, v17
	v_max3_f32 v50, v50, v15, v30
	v_max3_f32 v51, v51, v32, v33
	v_max3_f32 v50, v50, v31, v51
	ds_bpermute_b32 v51, v205, v50
	s_waitcnt lgkmcnt(0)
	v_max_f32_e32 v51, v51, v51
	v_max_f32_e32 v221, v50, v51
	v_sub_f32_e32 v2, v2, v221
	v_sub_f32_e32 v3, v3, v221
	v_sub_f32_e32 v18, v18, v221
	v_sub_f32_e32 v19, v19, v221
	v_exp_f32_e32 v2, v2
	v_exp_f32_e32 v3, v3
	v_sub_f32_e32 v4, v4, v221
	v_sub_f32_e32 v5, v5, v221
	v_sub_f32_e32 v50, v6, v221
	v_sub_f32_e32 v51, v7, v221
	v_exp_f32_e32 v6, v18
	v_exp_f32_e32 v7, v19
	v_sub_f32_e32 v20, v20, v221
	v_sub_f32_e32 v21, v21, v221
	v_exp_f32_e32 v4, v4
	v_exp_f32_e32 v5, v5
	v_sub_f32_e32 v52, v8, v221
	v_sub_f32_e32 v53, v9, v221
	v_exp_f32_e32 v8, v20
	v_exp_f32_e32 v9, v21
	v_sub_f32_e32 v22, v22, v221
	v_sub_f32_e32 v23, v23, v221
	v_sub_f32_e32 v54, v10, v221
	v_sub_f32_e32 v55, v11, v221
	v_exp_f32_e32 v10, v50
	v_exp_f32_e32 v11, v51
	v_pk_add_f32 v[50:51], v[2:3], 0 op_sel_hi:[1,0]
	v_sub_f32_e32 v56, v12, v221
	v_sub_f32_e32 v57, v13, v221
	v_exp_f32_e32 v12, v22
	v_exp_f32_e32 v13, v23
	v_pk_add_f32 v[50:51], v[6:7], v[50:51]
	v_sub_f32_e32 v24, v24, v221
	v_sub_f32_e32 v25, v25, v221
	v_sub_f32_e32 v58, v14, v221
	v_sub_f32_e32 v59, v15, v221
	v_exp_f32_e32 v14, v52
	v_exp_f32_e32 v15, v53
	v_pk_add_f32 v[50:51], v[4:5], v[50:51]
	v_sub_f32_e32 v60, v16, v221
	v_sub_f32_e32 v61, v17, v221
	v_exp_f32_e32 v16, v24
	v_exp_f32_e32 v17, v25
	v_pk_add_f32 v[50:51], v[8:9], v[50:51]
	v_sub_f32_e32 v26, v26, v221
	v_sub_f32_e32 v27, v27, v221
	v_exp_f32_e32 v18, v54
	v_exp_f32_e32 v19, v55
	v_pk_add_f32 v[50:51], v[10:11], v[50:51]
	v_exp_f32_e32 v20, v26
	v_exp_f32_e32 v21, v27
	v_pk_add_f32 v[50:51], v[12:13], v[50:51]
	v_sub_f32_e32 v28, v28, v221
	v_sub_f32_e32 v29, v29, v221
	v_exp_f32_e32 v22, v56
	v_exp_f32_e32 v23, v57
	v_pk_add_f32 v[50:51], v[14:15], v[50:51]
	v_exp_f32_e32 v24, v28
	v_exp_f32_e32 v25, v29
	v_pk_add_f32 v[50:51], v[16:17], v[50:51]
	v_sub_f32_e32 v30, v30, v221
	v_sub_f32_e32 v31, v31, v221
	v_exp_f32_e32 v26, v58
	v_exp_f32_e32 v27, v59
	v_pk_add_f32 v[50:51], v[18:19], v[50:51]
	v_exp_f32_e32 v28, v30
	v_exp_f32_e32 v29, v31
	v_pk_add_f32 v[50:51], v[20:21], v[50:51]
	v_sub_f32_e32 v32, v32, v221
	v_sub_f32_e32 v33, v33, v221
	v_exp_f32_e32 v30, v60
	v_exp_f32_e32 v31, v61
	v_pk_add_f32 v[50:51], v[22:23], v[50:51]
	v_exp_f32_e32 v32, v32
	v_exp_f32_e32 v33, v33
	v_pk_add_f32 v[50:51], v[24:25], v[50:51]
	v_xor_b32_e32 v66, 0x80000000, v221
	v_pk_add_f32 v[50:51], v[26:27], v[50:51]
	v_mov_b32_e32 v67, v66
	v_pk_add_f32 v[50:51], v[28:29], v[50:51]
	v_cvt_pk_bf16_f32 v2, v2, v3
	v_pk_add_f32 v[50:51], v[30:31], v[50:51]
	v_cvt_pk_bf16_f32 v3, v4, v5
	v_pk_add_f32 v[50:51], v[32:33], v[50:51]
	v_cvt_pk_bf16_f32 v4, v10, v11
	v_add_f32_e32 v158, v50, v51
	v_cvt_pk_bf16_f32 v5, v14, v15
	v_cvt_pk_bf16_f32 v98, v18, v19
	v_cvt_pk_bf16_f32 v99, v22, v23
	v_cvt_pk_bf16_f32 v100, v26, v27
	v_cvt_pk_bf16_f32 v101, v30, v31
	v_cvt_pk_bf16_f32 v102, v6, v7
	v_cvt_pk_bf16_f32 v103, v8, v9
	v_cvt_pk_bf16_f32 v104, v12, v13
	v_cvt_pk_bf16_f32 v105, v16, v17
	v_cvt_pk_bf16_f32 v106, v20, v21
	v_cvt_pk_bf16_f32 v107, v24, v25
	v_cvt_pk_bf16_f32 v108, v28, v29
	v_cvt_pk_bf16_f32 v109, v32, v33
	v_mov_b32_e32 v68, v66
	v_mov_b32_e32 v69, v66
	v_mov_b32_e32 v70, v66
	v_mov_b32_e32 v71, v66
	v_mov_b32_e32 v72, v66
	v_mov_b32_e32 v73, v66
	v_mov_b32_e32 v74, v66
	v_mov_b32_e32 v75, v66
	v_mov_b32_e32 v76, v66
	v_mov_b32_e32 v77, v66
	v_mov_b32_e32 v78, v66
	v_mov_b32_e32 v79, v66
	v_mov_b32_e32 v80, v66
	v_mov_b32_e32 v81, v66
	v_mfma_f32_32x32x16_bf16 v[50:65], v[34:37], v[2:5], 0
	ds_read_b128 v[6:9], v0 offset:22016
	ds_read_b128 v[10:13], v0 offset:22048
	ds_read_b128 v[14:17], v0 offset:22080
	ds_read_b128 v[18:21], v0 offset:22112
	v_mfma_f32_32x32x16_bf16 v[50:65], v[38:41], v[98:101], v[50:65]
	v_mfma_f32_32x32x16_bf16 v[50:65], v[42:45], v[102:105], v[50:65]
	v_mfma_f32_32x32x16_bf16 v[50:65], v[46:49], v[106:109], v[50:65]
	s_waitcnt lgkmcnt(3)
	v_mfma_f32_32x32x16_bf16 v[34:49], v[6:9], v[2:5], 0
	s_waitcnt lgkmcnt(2)
	v_mfma_f32_32x32x16_bf16 v[34:49], v[10:13], v[98:101], v[34:49]
	s_waitcnt lgkmcnt(1)
	v_mfma_f32_32x32x16_bf16 v[34:49], v[14:17], v[102:105], v[34:49]
	ds_read_b128 v[6:9], v0 offset:26624
	ds_read_b128 v[10:13], v0 offset:26656
	ds_read_b128 v[14:17], v0 offset:26688
	ds_read_b128 v[110:113], v0 offset:26720
	s_waitcnt lgkmcnt(4)
	v_mfma_f32_32x32x16_bf16 v[34:49], v[18:21], v[106:109], v[34:49]
	s_waitcnt lgkmcnt(3)
	v_mfma_f32_32x32x16_bf16 v[18:33], v[6:9], v[2:5], 0
	ds_read_b128 v[6:9], v0 offset:31232
	ds_read_b128 v[146:149], v0 offset:31264
	ds_read_b128 v[150:153], v0 offset:31296
	ds_read_b128 v[154:157], v0 offset:31328
	s_waitcnt lgkmcnt(6)
	v_mfma_f32_32x32x16_bf16 v[18:33], v[10:13], v[98:101], v[18:33]
	s_waitcnt lgkmcnt(5)
	v_mfma_f32_32x32x16_bf16 v[18:33], v[14:17], v[102:105], v[18:33]
	s_waitcnt lgkmcnt(4)
	v_mfma_f32_32x32x16_bf16 v[18:33], v[110:113], v[106:109], v[18:33]
	s_waitcnt lgkmcnt(3)
	v_mfma_f32_32x32x16_bf16 v[2:17], v[6:9], v[2:5], 0
	s_waitcnt lgkmcnt(2)
	v_mfma_f32_32x32x16_bf16 v[2:17], v[146:149], v[98:101], v[2:17]
	s_waitcnt lgkmcnt(1)
	v_mfma_f32_32x32x16_bf16 v[2:17], v[150:153], v[102:105], v[2:17]
	s_waitcnt lgkmcnt(0)
	v_mfma_f32_32x32x16_bf16 v[2:17], v[154:157], v[106:109], v[2:17]
	s_waitcnt vmcnt(3)
	ds_write_b128 v207, v[82:85] offset:35840
	s_waitcnt vmcnt(2)
	ds_write_b128 v208, v[86:89] offset:35840
	s_waitcnt vmcnt(1)
	ds_write_b128 v209, v[90:93] offset:53248
	s_waitcnt vmcnt(0)
	ds_write_b128 v210, v[94:97] offset:53248
	s_waitcnt lgkmcnt(0)
	s_barrier
; template <int DQK, int DV, int FLAGS, int qp, int kp, int vts, int op> ...
;     ...
;             const LAS unsigned char* kb = lds + cur * BUF + prow * KROW + 16 * hi;
;             const LAS unsigned char* vb = lds + cur * BUF + KT_BYTES + r32 * VROW + 16 * hi;
;             f32x16 p0, p1;
;             bf16x8 kf[2][4];
; #pragma unroll
;             for (int i = 0; i < 2; ++i) { kf[0][2 * i] = *(const LAS bf16x8*)(kb + i * 32); kf[0][2 * i + 1] = *(const LAS bf16x8*)(kb + 32 * KROW + i * 32); }
;             const int nrel = qpos - kv0 - 8 * hi;
;             if (FLAGS & AF_ALIBI) { const float ab = -slope2 * (float)nrel - ((FLAGS & AF_ROBUST) ? 0.f : m);
; #pragma unroll
;                 for (int r = 0; r < 16; ++r) { const float c = (float)(16 * (r >> 3) + (r & 7)); p0[r] = __builtin_fmaf(slope2, c, ab); p1[r] = __builtin_fmaf(slope2, c + 32.f, ab); }
;             } else if (FLAGS & AF_ROBUST) {
; #pragma unroll
;                 for (int r = 0; r < 16; ++r) { p0[r] = 0.f; p1[r] = 0.f; }
;             } else { p0 = negm; p1 = negm; }
;             __builtin_amdgcn_sched_barrier(0);
; #pragma unroll
;             for (int c = 0; c < ND0 / 2; ++c) {
;                 if (c + 1 < ND0 / 2) {
; #pragma unroll
;                     for (int i = 0; i < 2; ++i) { kf[(c + 1) & 1][2 * i] = *(const LAS bf16x8*)(kb + (2 * c + 2 + i) * 32); kf[(c + 1) & 1][2 * i + 1] = *(const LAS bf16x8*)(kb + 32 * KROW + (2 * c + 2 + i) * 32); }
;                 }
; #pragma unroll
;                 for (int i = 0; i < 2; ++i) {
;                     p0 = __builtin_amdgcn_mfma_f32_32x32x16_bf16(kf[c & 1][2 * i], qr[2 * c + i], p0, 0, 0, 0);
;                     p1 = __builtin_amdgcn_mfma_f32_32x32x16_bf16(kf[c & 1][2 * i + 1], qr[2 * c + i], p1, 0, 0, 0);
;                 }
;                 __builtin_amdgcn_sched_barrier(0);
;             }
;     ...
;             if ((FLAGS & AF_ROBUST) || !started || !skipmax) {
;               float a = MX3(p0[0], p0[1], p1[0]), b = MX3(p0[2], p0[3], p1[1]); a = MX3(a, p1[2], p1[3]);
; #pragma unroll
;               for (int r = 4; r < 16; r += 4) { a = MX3(a, p0[r], p0[r + 1]); b = MX3(b, p0[r + 2], p0[r + 3]); a = MX3(a, p1[r], p1[r + 1]); b = MX3(b, p1[r + 2], p1[r + 3]); }
;               mx = __builtin_fmaxf(a, b);
;               if ((FLAGS & AF_ROBUST) || !started) mx = __builtin_fmaxf(mx, shfl_xor_l(mx, 32, lane)); }
	ds_read_b128 v[82:85], v206 offset:35840
	ds_read_b128 v[146:149], v206 offset:35872
	ds_read_b128 v[150:153], v206 offset:44544
	ds_read_b128 v[154:157], v206 offset:44576
	v_add_f32_e32 v222, 0, v158
	s_waitcnt lgkmcnt(3)
	v_mfma_f32_32x32x16_bf16 v[98:113], v[82:85], v[114:117], v[66:81]
	v_mov_b64_e32 v[96:97], v[80:81]
	v_mov_b64_e32 v[94:95], v[78:79]
	v_mov_b64_e32 v[92:93], v[76:77]
	v_mov_b64_e32 v[90:91], v[74:75]
	v_mov_b64_e32 v[88:89], v[72:73]
	v_mov_b64_e32 v[86:87], v[70:71]
	v_mov_b64_e32 v[84:85], v[68:69]
	v_mov_b64_e32 v[82:83], v[66:67]
	s_waitcnt lgkmcnt(2)
	v_mfma_f32_32x32x16_bf16 v[98:113], v[146:149], v[118:121], v[98:113]
	ds_read_b128 v[68:71], v206 offset:35904
	ds_read_b128 v[72:75], v206 offset:35936
	ds_read_b128 v[76:79], v206 offset:44608
	ds_read_b128 v[146:149], v206 offset:44640
	s_waitcnt lgkmcnt(5)
	v_mfma_f32_32x32x16_bf16 v[82:97], v[150:153], v[114:117], v[82:97]
	s_waitcnt lgkmcnt(4)
	v_mfma_f32_32x32x16_bf16 v[82:97], v[154:157], v[118:121], v[82:97]
	s_waitcnt lgkmcnt(3)
	v_mfma_f32_32x32x16_bf16 v[98:113], v[68:71], v[122:125], v[98:113]
	s_waitcnt lgkmcnt(1)
	v_mfma_f32_32x32x16_bf16 v[82:97], v[76:79], v[122:125], v[82:97]
	v_mfma_f32_32x32x16_bf16 v[98:113], v[72:75], v[126:129], v[98:113]
	ds_read_b128 v[68:71], v206 offset:35968
	ds_read_b128 v[72:75], v206 offset:36000
	ds_read_b128 v[76:79], v206 offset:44672
	ds_read_b128 v[150:153], v206 offset:44704
	s_waitcnt lgkmcnt(4)
	v_mfma_f32_32x32x16_bf16 v[82:97], v[146:149], v[126:129], v[82:97]
	s_waitcnt lgkmcnt(3)
	v_mfma_f32_32x32x16_bf16 v[98:113], v[68:71], v[130:133], v[98:113]
	s_waitcnt lgkmcnt(1)
	v_mfma_f32_32x32x16_bf16 v[82:97], v[76:79], v[130:133], v[82:97]
	v_mfma_f32_32x32x16_bf16 v[98:113], v[72:75], v[134:137], v[98:113]
	ds_read_b128 v[68:71], v206 offset:36032
	ds_read_b128 v[72:75], v206 offset:36064
	ds_read_b128 v[76:79], v206 offset:44736
	ds_read_b128 v[146:149], v206 offset:44768
	s_waitcnt lgkmcnt(4)
	v_mfma_f32_32x32x16_bf16 v[82:97], v[150:153], v[134:137], v[82:97]
	s_waitcnt lgkmcnt(3)
	v_mfma_f32_32x32x16_bf16 v[98:113], v[68:71], v[138:141], v[98:113]
	s_waitcnt lgkmcnt(1)
	v_mfma_f32_32x32x16_bf16 v[82:97], v[76:79], v[138:141], v[82:97]
	v_mfma_f32_32x32x16_bf16 v[98:113], v[72:75], v[142:145], v[98:113]
	s_waitcnt lgkmcnt(0)
	v_mfma_f32_32x32x16_bf16 v[82:97], v[146:149], v[142:145], v[82:97]
	s_add_u32 s2, s40, 0x20000
	s_addc_u32 s3, s41, 0
	global_load_dwordx4 v[146:149], v196, s[2:3]
	global_load_dwordx4 v[150:153], v198, s[2:3]
	global_load_dwordx4 v[154:157], v200, s[42:43] offset:256
	global_load_dwordx4 v[158:161], v202, s[42:43] offset:256
	ds_read_b128 v[174:177], v0 offset:53248
	ds_read_b128 v[170:173], v0 offset:53280
	ds_read_b128 v[166:169], v0 offset:53312
	ds_read_b128 v[162:165], v0 offset:53344
	v_max_f32_e32 v67, v99, v99
	v_max_f32_e32 v68, v98, v98
	v_max_f32_e32 v67, v68, v67
	v_max3_f32 v68, v100, v101, v83
	v_max3_f32 v67, v67, v82, v84
	v_max3_f32 v67, v67, v85, v102
	v_max3_f32 v68, v68, v104, v105
	v_max3_f32 v67, v67, v103, v86
	v_max3_f32 v68, v68, v88, v89
	v_max3_f32 v67, v67, v87, v106
	v_max3_f32 v68, v68, v108, v109
	v_max3_f32 v67, v67, v107, v90
	v_max3_f32 v68, v68, v92, v93
	v_max3_f32 v67, v67, v91, v110
	v_max3_f32 v68, v68, v112, v113
	v_max3_f32 v67, v67, v111, v94
	v_max3_f32 v68, v68, v96, v97
	v_max3_f32 v67, v67, v95, v68
	v_cmp_lt_f32_e32 vcc, s38, v67
	s_cbranch_vccz .LBB0_1284
	ds_bpermute_b32 v66, v205, v67
	s_waitcnt lgkmcnt(0)
	v_max3_f32 v66, v67, v66, 0
	v_exp_f32_e64 v68, -v66
	v_add_f32_e32 v221, v221, v66
	v_pk_add_f32 v[98:99], v[98:99], v[66:67] op_sel_hi:[1,0] neg_lo:[0,1] neg_hi:[0,1]
	v_pk_add_f32 v[82:83], v[82:83], v[66:67] op_sel_hi:[1,0] neg_lo:[0,1] neg_hi:[0,1]
	v_pk_add_f32 v[100:101], v[100:101], v[66:67] op_sel_hi:[1,0] neg_lo:[0,1] neg_hi:[0,1]
	v_pk_add_f32 v[84:85], v[84:85], v[66:67] op_sel_hi:[1,0] neg_lo:[0,1] neg_hi:[0,1]
	v_pk_add_f32 v[102:103], v[102:103], v[66:67] op_sel_hi:[1,0] neg_lo:[0,1] neg_hi:[0,1]
	v_pk_add_f32 v[86:87], v[86:87], v[66:67] op_sel_hi:[1,0] neg_lo:[0,1] neg_hi:[0,1]
	v_pk_add_f32 v[104:105], v[104:105], v[66:67] op_sel_hi:[1,0] neg_lo:[0,1] neg_hi:[0,1]
	v_pk_add_f32 v[88:89], v[88:89], v[66:67] op_sel_hi:[1,0] neg_lo:[0,1] neg_hi:[0,1]
	v_pk_add_f32 v[106:107], v[106:107], v[66:67] op_sel_hi:[1,0] neg_lo:[0,1] neg_hi:[0,1]
	v_pk_add_f32 v[90:91], v[90:91], v[66:67] op_sel_hi:[1,0] neg_lo:[0,1] neg_hi:[0,1]
	v_pk_add_f32 v[108:109], v[108:109], v[66:67] op_sel_hi:[1,0] neg_lo:[0,1] neg_hi:[0,1]
	v_pk_add_f32 v[92:93], v[92:93], v[66:67] op_sel_hi:[1,0] neg_lo:[0,1] neg_hi:[0,1]
	v_pk_add_f32 v[110:111], v[110:111], v[66:67] op_sel_hi:[1,0] neg_lo:[0,1] neg_hi:[0,1]
	v_pk_add_f32 v[94:95], v[94:95], v[66:67] op_sel_hi:[1,0] neg_lo:[0,1] neg_hi:[0,1]
	v_pk_add_f32 v[112:113], v[112:113], v[66:67] op_sel_hi:[1,0] neg_lo:[0,1] neg_hi:[0,1]
	v_pk_add_f32 v[96:97], v[96:97], v[66:67] op_sel_hi:[1,0] neg_lo:[0,1] neg_hi:[0,1]
	v_pk_mul_f32 v[64:65], v[64:65], v[68:69] op_sel_hi:[1,0]
	v_pk_mul_f32 v[62:63], v[62:63], v[68:69] op_sel_hi:[1,0]
	v_pk_mul_f32 v[60:61], v[60:61], v[68:69] op_sel_hi:[1,0]
	v_pk_mul_f32 v[58:59], v[58:59], v[68:69] op_sel_hi:[1,0]
	v_pk_mul_f32 v[56:57], v[56:57], v[68:69] op_sel_hi:[1,0]
	v_pk_mul_f32 v[54:55], v[54:55], v[68:69] op_sel_hi:[1,0]
	v_pk_mul_f32 v[52:53], v[52:53], v[68:69] op_sel_hi:[1,0]
	v_pk_mul_f32 v[50:51], v[50:51], v[68:69] op_sel_hi:[1,0]
	v_pk_mul_f32 v[48:49], v[48:49], v[68:69] op_sel_hi:[1,0]
	v_pk_mul_f32 v[46:47], v[46:47], v[68:69] op_sel_hi:[1,0]
	v_pk_mul_f32 v[44:45], v[44:45], v[68:69] op_sel_hi:[1,0]
	v_pk_mul_f32 v[42:43], v[42:43], v[68:69] op_sel_hi:[1,0]
	v_pk_mul_f32 v[40:41], v[40:41], v[68:69] op_sel_hi:[1,0]
	v_pk_mul_f32 v[38:39], v[38:39], v[68:69] op_sel_hi:[1,0]
	v_pk_mul_f32 v[36:37], v[36:37], v[68:69] op_sel_hi:[1,0]
	v_pk_mul_f32 v[34:35], v[34:35], v[68:69] op_sel_hi:[1,0]
	v_pk_mul_f32 v[32:33], v[32:33], v[68:69] op_sel_hi:[1,0]
	v_pk_mul_f32 v[30:31], v[30:31], v[68:69] op_sel_hi:[1,0]
	v_pk_mul_f32 v[28:29], v[28:29], v[68:69] op_sel_hi:[1,0]
	v_pk_mul_f32 v[26:27], v[26:27], v[68:69] op_sel_hi:[1,0]
	v_pk_mul_f32 v[24:25], v[24:25], v[68:69] op_sel_hi:[1,0]
	v_pk_mul_f32 v[22:23], v[22:23], v[68:69] op_sel_hi:[1,0]
	v_pk_mul_f32 v[20:21], v[20:21], v[68:69] op_sel_hi:[1,0]
	v_pk_mul_f32 v[18:19], v[18:19], v[68:69] op_sel_hi:[1,0]
	v_pk_mul_f32 v[16:17], v[16:17], v[68:69] op_sel_hi:[1,0]
	v_pk_mul_f32 v[14:15], v[14:15], v[68:69] op_sel_hi:[1,0]
	v_pk_mul_f32 v[12:13], v[12:13], v[68:69] op_sel_hi:[1,0]
	v_pk_mul_f32 v[10:11], v[10:11], v[68:69] op_sel_hi:[1,0]
	v_pk_mul_f32 v[8:9], v[8:9], v[68:69] op_sel_hi:[1,0]
	v_pk_mul_f32 v[6:7], v[6:7], v[68:69] op_sel_hi:[1,0]
	v_pk_mul_f32 v[4:5], v[4:5], v[68:69] op_sel_hi:[1,0]
	v_pk_mul_f32 v[2:3], v[2:3], v[68:69] op_sel_hi:[1,0]
	v_xor_b32_e32 v66, 0x80000000, v221
	v_mul_f32_e32 v222, v222, v68
